# ph10 rope epilogue: 8-byte store pairs merged into 16-byte stores via v_permlane16_swap (same bytes), vmcnt recounted
# speedup vs baseline: 1.0109x; 1.0079x over previous
; __device__ __forceinline__ unsigned cvt_pk_bf16(float lo, float hi) { unsigned r; asm volatile("v_cvt_pk_bf16_f32 %0, %1, %2" : "=v"(r) : "v"(lo), "v"(hi)); return r; }
;     __device__ __forceinline__ void operator()(const pg8::f32x4 (&acc)[2][2][4][2], const Unit& u, int wr, int wc, int fr, int fq) const {
;     ...
;         if (pn < rope_tiles) {
;             const float s_ = (pn >= sc_lo && pn < sc_hi) ? sc : 1.f;
;             const int i0 = 16 * (wc & 1) + 4 * fq;
;             f32x4 cN = *(const f32x4*)(cs + (row0 & (SEQL - 1)) * 64 + i0), sN = *(const f32x4*)(cs + (row0 & (SEQL - 1)) * 64 + 32 + i0);
; #pragma unroll
;             for (int k = 0; k < 8; ++k) { const int ai = k >> 2, m = k & 3; const int row = row0 + ai * HALF + m * 16; const float s = s_ * rsv[k];
;                 const f32x4 c = cN, sn = sN;
;                 if (k < 7) { const int rown = row0 + ((k + 1) >> 2) * HALF + ((k + 1) & 3) * 16, posn = rown & (SEQL - 1); cN = *(const f32x4*)(cs + posn * 64 + i0); sN = *(const f32x4*)(cs + posn * 64 + 32 + i0); }
; #pragma unroll
;                 for (int bj = 0; bj < 2; ++bj) { const f32x4 x1 = acc[ai][bj][m][0], x2 = acc[ai][bj][m][1];
;                     const f32x4 o1 = (x1 * c - x2 * sn) * s, o2 = (x2 * c + x1 * sn) * s;
;                     bf16* p = Ob + (size_t)row * ldc + pt * BM + bj * HALF + 64 * (wc >> 1) + i0;
;                     v2u w1, w2; w1.x = cvt_pk_bf16(o1[0], o1[1]); w1.y = cvt_pk_bf16(o1[2], o1[3]); w2.x = cvt_pk_bf16(o2[0], o2[1]); w2.y = cvt_pk_bf16(o2[2], o2[3]);
;                     *(v2u*)p = w1; *(v2u*)(p + 32) = w2; } }
.LBB0_996:
	v_mbcnt_lo_u32_b32 v252, -1, 0
	v_mbcnt_hi_u32_b32 v252, -1, v252
	v_bfe_u32 v252, v252, 4, 1
	v_mul_u32_u24_e32 v252, 56, v252
	v_mov_b32_e32 v253, 0
	v_lshlrev_b32_e32 v138, 8, v174
	v_and_b32_e32 v138, 0xfcf00, v138
	v_lshl_add_u64 v[174:175], s[10:11], 0, v[138:139]
	v_lshlrev_b32_e32 v138, 2, v140
	v_lshl_add_u64 v[174:175], v[174:175], 0, v[138:139]
	v_add_co_u32_e32 v192, vcc, s53, v174
	global_load_dwordx4 v[184:187], v[174:175], off offset:128
	global_load_dwordx4 v[188:191], v[174:175], off
	v_addc_co_u32_e32 v193, vcc, 0, v175, vcc
	v_add_co_u32_e32 v200, vcc, s42, v174
	global_load_dwordx4 v[192:195], v[192:193], off offset:128
	s_nop 0
	v_addc_co_u32_e32 v201, vcc, 0, v175, vcc
	global_load_dwordx4 v[196:199], v[200:201], off offset:-4096
	s_cmp_lt_u32 s0, 4
	s_cselect_b64 vcc, -1, 0
	s_lshl_b32 s4, s19, 8
	s_ashr_i32 s5, s4, 31
	s_lshl_b64 s[4:5], s[4:5], 1
	s_add_u32 s0, s17, s4
	s_addc_u32 s1, s1, s5
	s_add_u32 s0, s0, s52
	v_lshlrev_b32_e32 v202, 1, v140
	v_mov_b32_e32 v203, v139
	v_cndmask_b32_e32 v153, 1.0, v173, vcc
	v_add_co_u32_e32 v204, vcc, s54, v174
	s_addc_u32 s1, s1, 0
	s_nop 0
	v_addc_co_u32_e32 v205, vcc, 0, v175, vcc
	v_lshl_add_u64 v[174:175], s[0:1], 0, v[202:203]
	v_mul_f32_e32 v182, v153, v182
	v_lshl_add_u64 v[176:177], v[174:175], 0, v[176:177]
	v_lshl_add_u64 v[176:177], v[176:177], 0, v[252:253]
	v_mul_f32_e32 v180, v153, v180
	v_lshl_add_u64 v[178:179], v[174:175], 0, v[178:179]
	v_lshl_add_u64 v[178:179], v[178:179], 0, v[252:253]
	s_waitcnt vmcnt(3)
	v_pk_mul_f32 v[202:203], v[124:125], v[186:187]
	v_pk_mul_f32 v[206:207], v[122:123], v[184:185]
	v_pk_mul_f32 v[208:209], v[128:129], v[186:187]
	v_pk_mul_f32 v[210:211], v[126:127], v[184:185]
	v_pk_mul_f32 v[212:213], v[116:117], v[186:187]
	v_pk_mul_f32 v[214:215], v[114:115], v[184:185]
	v_pk_mul_f32 v[186:187], v[120:121], v[186:187]
	v_pk_mul_f32 v[184:185], v[118:119], v[184:185]
	s_waitcnt vmcnt(2)
	v_pk_fma_f32 v[128:129], v[128:129], v[190:191], v[202:203] neg_lo:[0,0,1] neg_hi:[0,0,1]
	v_pk_fma_f32 v[126:127], v[126:127], v[188:189], v[206:207] neg_lo:[0,0,1] neg_hi:[0,0,1]
	v_pk_fma_f32 v[124:125], v[124:125], v[190:191], v[208:209]
	v_pk_fma_f32 v[122:123], v[122:123], v[188:189], v[210:211]
	v_pk_fma_f32 v[120:121], v[120:121], v[190:191], v[212:213] neg_lo:[0,0,1] neg_hi:[0,0,1]
	v_pk_fma_f32 v[118:119], v[118:119], v[188:189], v[214:215] neg_lo:[0,0,1] neg_hi:[0,0,1]
	v_pk_fma_f32 v[116:117], v[116:117], v[190:191], v[186:187]
	v_pk_fma_f32 v[114:115], v[114:115], v[188:189], v[184:185]
	s_waitcnt vmcnt(1)
	v_pk_mul_f32 v[184:185], v[108:109], v[194:195]
	v_pk_mul_f32 v[188:189], v[112:113], v[194:195]
	v_pk_mul_f32 v[128:129], v[182:183], v[128:129] op_sel_hi:[0,1]
	v_pk_mul_f32 v[126:127], v[182:183], v[126:127] op_sel_hi:[0,1]
	v_pk_mul_f32 v[124:125], v[182:183], v[124:125] op_sel_hi:[0,1]
	v_pk_mul_f32 v[122:123], v[182:183], v[122:123] op_sel_hi:[0,1]
	v_pk_mul_f32 v[120:121], v[182:183], v[120:121] op_sel_hi:[0,1]
	v_pk_mul_f32 v[118:119], v[182:183], v[118:119] op_sel_hi:[0,1]
	v_pk_mul_f32 v[116:117], v[182:183], v[116:117] op_sel_hi:[0,1]
	v_pk_mul_f32 v[114:115], v[182:183], v[114:115] op_sel_hi:[0,1]
	s_waitcnt vmcnt(0)
	v_pk_fma_f32 v[182:183], v[112:113], v[198:199], v[184:185] neg_lo:[0,0,1] neg_hi:[0,0,1]
	v_cvt_pk_bf16_f32 v240, v126, v127
	v_cvt_pk_bf16_f32 v241, v128, v129
	v_pk_mul_f32 v[186:187], v[106:107], v[192:193]
	v_cvt_pk_bf16_f32 v242, v122, v123
	v_cvt_pk_bf16_f32 v243, v124, v125
	s_nop 1
	v_permlane16_swap_b32 v240, v242
	v_permlane16_swap_b32 v241, v243
	global_store_dwordx4 v[176:177], v[240:243], off
	v_cvt_pk_bf16_f32 v244, v118, v119
	v_cvt_pk_bf16_f32 v245, v120, v121
	v_pk_mul_f32 v[190:191], v[110:111], v[192:193]
	v_pk_mul_f32 v[206:207], v[98:99], v[192:193]
	v_cvt_pk_bf16_f32 v246, v114, v115
	v_cvt_pk_bf16_f32 v247, v116, v117
	s_nop 1
	v_permlane16_swap_b32 v244, v246
	v_permlane16_swap_b32 v245, v247
	global_store_dwordx4 v[176:177], v[244:247], off offset:256
	v_pk_fma_f32 v[110:111], v[110:111], v[196:197], v[186:187] neg_lo:[0,0,1] neg_hi:[0,0,1]
	v_pk_mul_f32 v[202:203], v[100:101], v[194:195]
	v_pk_mul_f32 v[192:193], v[102:103], v[192:193]
	global_load_dwordx4 v[112:115], v[200:201], off
	global_load_dwordx4 v[116:119], v[200:201], off offset:128
	v_pk_fma_f32 v[106:107], v[106:107], v[196:197], v[190:191]
	v_pk_fma_f32 v[102:103], v[102:103], v[196:197], v[206:207] neg_lo:[0,0,1] neg_hi:[0,0,1]
	v_pk_mul_f32 v[110:111], v[180:181], v[110:111] op_sel_hi:[0,1]
	v_pk_mul_f32 v[194:195], v[104:105], v[194:195]
	v_pk_fma_f32 v[108:109], v[108:109], v[198:199], v[188:189]
	v_pk_fma_f32 v[104:105], v[104:105], v[198:199], v[202:203] neg_lo:[0,0,1] neg_hi:[0,0,1]
	v_pk_fma_f32 v[98:99], v[98:99], v[196:197], v[192:193]
	v_pk_mul_f32 v[120:121], v[180:181], v[182:183] op_sel_hi:[0,1]
	v_pk_mul_f32 v[106:107], v[180:181], v[106:107] op_sel_hi:[0,1]
	v_pk_mul_f32 v[102:103], v[180:181], v[102:103] op_sel_hi:[0,1]
	v_cvt_pk_bf16_f32 v248, v110, v111
	v_cvt_pk_bf16_f32 v249, v120, v121
	v_pk_fma_f32 v[100:101], v[100:101], v[198:199], v[194:195]
	v_pk_mul_f32 v[108:109], v[180:181], v[108:109] op_sel_hi:[0,1]
	v_pk_mul_f32 v[104:105], v[180:181], v[104:105] op_sel_hi:[0,1]
	v_pk_mul_f32 v[98:99], v[180:181], v[98:99] op_sel_hi:[0,1]
	v_cvt_pk_bf16_f32 v250, v106, v107
	v_cvt_pk_bf16_f32 v251, v108, v109
	s_nop 1
	v_permlane16_swap_b32 v248, v250
	v_permlane16_swap_b32 v249, v251
	global_store_dwordx4 v[178:179], v[248:251], off
	v_cvt_pk_bf16_f32 v240, v102, v103
	v_cvt_pk_bf16_f32 v241, v104, v105
	v_pk_mul_f32 v[100:101], v[180:181], v[100:101] op_sel_hi:[0,1]
	v_cvt_pk_bf16_f32 v242, v98, v99
	v_cvt_pk_bf16_f32 v243, v100, v101
	s_nop 1
	v_permlane16_swap_b32 v240, v242
	v_permlane16_swap_b32 v241, v243
	global_store_dwordx4 v[178:179], v[240:243], off offset:256
	global_load_dwordx4 v[100:103], v[204:205], off offset:128
	s_nop 0
	global_load_dwordx4 v[104:107], v[204:205], off
	v_mul_f32_e32 v108, v153, v170
	v_lshl_add_u64 v[122:123], v[174:175], 0, v[166:167]
	v_lshl_add_u64 v[122:123], v[122:123], 0, v[252:253]
	v_lshl_add_u64 v[124:125], v[174:175], 0, v[168:169]
	v_lshl_add_u64 v[124:125], v[124:125], 0, v[252:253]
	v_lshlrev_b32_e32 v98, 8, v154
	v_mov_b32_e32 v99, v139
	v_and_b32_e32 v98, 0xfcf00, v98
	v_mul_f32_e32 v110, v153, v172
	v_lshl_add_u64 v[98:99], s[10:11], 0, v[98:99]
	v_lshl_add_u64 v[98:99], v[98:99], 0, v[138:139]
	v_add_co_u32_e32 v120, vcc, s53, v98
	s_waitcnt vmcnt(4)
; __device__ __forceinline__ unsigned cvt_pk_bf16(float lo, float hi) { unsigned r; asm volatile("v_cvt_pk_bf16_f32 %0, %1, %2" : "=v"(r) : "v"(lo), "v"(hi)); return r; }
;     __device__ __forceinline__ void operator()(const pg8::f32x4 (&acc)[2][2][4][2], const Unit& u, int wr, int wc, int fr, int fq) const {
;     ...
;         if (pn < rope_tiles) {
;             const float s_ = (pn >= sc_lo && pn < sc_hi) ? sc : 1.f;
;             const int i0 = 16 * (wc & 1) + 4 * fq;
;             f32x4 cN = *(const f32x4*)(cs + (row0 & (SEQL - 1)) * 64 + i0), sN = *(const f32x4*)(cs + (row0 & (SEQL - 1)) * 64 + 32 + i0);
; #pragma unroll
;             for (int k = 0; k < 8; ++k) { const int ai = k >> 2, m = k & 3; const int row = row0 + ai * HALF + m * 16; const float s = s_ * rsv[k];
;                 const f32x4 c = cN, sn = sN;
;                 if (k < 7) { const int rown = row0 + ((k + 1) >> 2) * HALF + ((k + 1) & 3) * 16, posn = rown & (SEQL - 1); cN = *(const f32x4*)(cs + posn * 64 + i0); sN = *(const f32x4*)(cs + posn * 64 + 32 + i0); }
; #pragma unroll
;                 for (int bj = 0; bj < 2; ++bj) { const f32x4 x1 = acc[ai][bj][m][0], x2 = acc[ai][bj][m][1];
;                     const f32x4 o1 = (x1 * c - x2 * sn) * s, o2 = (x2 * c + x1 * sn) * s;
;                     bf16* p = Ob + (size_t)row * ldc + pt * BM + bj * HALF + 64 * (wc >> 1) + i0;
;                     v2u w1, w2; w1.x = cvt_pk_bf16(o1[0], o1[1]); w1.y = cvt_pk_bf16(o1[2], o1[3]); w2.x = cvt_pk_bf16(o2[0], o2[1]); w2.y = cvt_pk_bf16(o2[2], o2[3]);
;                     *(v2u*)p = w1; *(v2u*)(p + 32) = w2; } }
	v_pk_mul_f32 v[126:127], v[92:93], v[118:119]
	v_pk_mul_f32 v[128:129], v[90:91], v[116:117]
	v_pk_mul_f32 v[166:167], v[96:97], v[118:119]
	v_pk_mul_f32 v[168:169], v[94:95], v[116:117]
	v_pk_mul_f32 v[178:179], v[82:83], v[116:117]
	v_pk_fma_f32 v[96:97], v[96:97], v[114:115], v[126:127] neg_lo:[0,0,1] neg_hi:[0,0,1]
	v_pk_fma_f32 v[94:95], v[94:95], v[112:113], v[128:129] neg_lo:[0,0,1] neg_hi:[0,0,1]
	v_pk_mul_f32 v[176:177], v[84:85], v[118:119]
	v_pk_mul_f32 v[116:117], v[86:87], v[116:117]
	v_pk_fma_f32 v[92:93], v[92:93], v[114:115], v[166:167]
	v_pk_fma_f32 v[90:91], v[90:91], v[112:113], v[168:169]
	v_pk_fma_f32 v[86:87], v[86:87], v[112:113], v[178:179] neg_lo:[0,0,1] neg_hi:[0,0,1]
	v_pk_mul_f32 v[96:97], v[108:109], v[96:97] op_sel_hi:[0,1]
	v_pk_mul_f32 v[94:95], v[108:109], v[94:95] op_sel_hi:[0,1]
	v_pk_mul_f32 v[118:119], v[88:89], v[118:119]
	v_pk_fma_f32 v[88:89], v[88:89], v[114:115], v[176:177] neg_lo:[0,0,1] neg_hi:[0,0,1]
	v_pk_fma_f32 v[82:83], v[82:83], v[112:113], v[116:117]
	v_pk_mul_f32 v[92:93], v[108:109], v[92:93] op_sel_hi:[0,1]
	v_pk_mul_f32 v[90:91], v[108:109], v[90:91] op_sel_hi:[0,1]
	v_pk_mul_f32 v[86:87], v[108:109], v[86:87] op_sel_hi:[0,1]
	v_cvt_pk_bf16_f32 v244, v94, v95
	v_cvt_pk_bf16_f32 v245, v96, v97
	v_pk_fma_f32 v[84:85], v[84:85], v[114:115], v[118:119]
	v_pk_mul_f32 v[88:89], v[108:109], v[88:89] op_sel_hi:[0,1]
	v_pk_mul_f32 v[82:83], v[108:109], v[82:83] op_sel_hi:[0,1]
	s_waitcnt vmcnt(1)
	v_pk_mul_f32 v[96:97], v[74:75], v[100:101]
	v_cvt_pk_bf16_f32 v246, v90, v91
	v_cvt_pk_bf16_f32 v247, v92, v93
	v_pk_mul_f32 v[92:93], v[76:77], v[102:103]
	v_pk_mul_f32 v[112:113], v[78:79], v[100:101]
	v_pk_mul_f32 v[116:117], v[66:67], v[100:101]
	s_nop 1
	v_permlane16_swap_b32 v244, v246
	v_permlane16_swap_b32 v245, v247
	global_store_dwordx4 v[122:123], v[244:247], off
	v_cvt_pk_bf16_f32 v248, v86, v87
	v_cvt_pk_bf16_f32 v249, v88, v89
	s_waitcnt vmcnt(1)
	v_pk_fma_f32 v[78:79], v[78:79], v[104:105], v[96:97] neg_lo:[0,0,1] neg_hi:[0,0,1]
	v_pk_mul_f32 v[84:85], v[108:109], v[84:85] op_sel_hi:[0,1]
	v_pk_mul_f32 v[108:109], v[80:81], v[102:103]
	v_pk_mul_f32 v[114:115], v[68:69], v[102:103]
	v_pk_mul_f32 v[100:101], v[70:71], v[100:101]
	v_cvt_pk_bf16_f32 v250, v82, v83
	v_cvt_pk_bf16_f32 v251, v84, v85
	v_pk_fma_f32 v[88:89], v[80:81], v[106:107], v[92:93] neg_lo:[0,0,1] neg_hi:[0,0,1]
	s_nop 1
	v_permlane16_swap_b32 v248, v250
	v_permlane16_swap_b32 v249, v251
	global_store_dwordx4 v[122:123], v[248:251], off offset:256
	v_pk_fma_f32 v[74:75], v[74:75], v[104:105], v[112:113]
	v_pk_fma_f32 v[70:71], v[70:71], v[104:105], v[116:117] neg_lo:[0,0,1] neg_hi:[0,0,1]
	v_pk_mul_f32 v[78:79], v[110:111], v[78:79] op_sel_hi:[0,1]
	v_pk_mul_f32 v[102:103], v[72:73], v[102:103]
	global_load_dwordx4 v[80:83], v[98:99], off
	global_load_dwordx4 v[84:87], v[98:99], off offset:128
	v_pk_fma_f32 v[76:77], v[76:77], v[106:107], v[108:109]
	v_pk_fma_f32 v[72:73], v[72:73], v[106:107], v[114:115] neg_lo:[0,0,1] neg_hi:[0,0,1]
	v_pk_fma_f32 v[66:67], v[66:67], v[104:105], v[100:101]
	v_pk_mul_f32 v[88:89], v[110:111], v[88:89] op_sel_hi:[0,1]
	v_pk_mul_f32 v[74:75], v[110:111], v[74:75] op_sel_hi:[0,1]
	v_pk_mul_f32 v[70:71], v[110:111], v[70:71] op_sel_hi:[0,1]
	v_cvt_pk_bf16_f32 v240, v78, v79
	v_cvt_pk_bf16_f32 v241, v88, v89
	v_addc_co_u32_e32 v121, vcc, 0, v99, vcc
	v_pk_fma_f32 v[68:69], v[68:69], v[106:107], v[102:103]
	v_pk_mul_f32 v[76:77], v[110:111], v[76:77] op_sel_hi:[0,1]
	v_pk_mul_f32 v[72:73], v[110:111], v[72:73] op_sel_hi:[0,1]
	v_pk_mul_f32 v[66:67], v[110:111], v[66:67] op_sel_hi:[0,1]
	v_cvt_pk_bf16_f32 v242, v74, v75
	v_cvt_pk_bf16_f32 v243, v76, v77
	s_nop 1
	v_permlane16_swap_b32 v240, v242
	v_permlane16_swap_b32 v241, v243
	global_store_dwordx4 v[124:125], v[240:243], off
	v_cvt_pk_bf16_f32 v244, v70, v71
	v_cvt_pk_bf16_f32 v245, v72, v73
	v_pk_mul_f32 v[68:69], v[110:111], v[68:69] op_sel_hi:[0,1]
	v_cvt_pk_bf16_f32 v246, v66, v67
	v_cvt_pk_bf16_f32 v247, v68, v69
	s_nop 1
	v_permlane16_swap_b32 v244, v246
	v_permlane16_swap_b32 v245, v247
	global_store_dwordx4 v[124:125], v[244:247], off offset:256
	v_add_co_u32_e32 v74, vcc, s42, v98
	global_load_dwordx4 v[66:69], v[120:121], off offset:128
	s_nop 0
	v_addc_co_u32_e32 v75, vcc, 0, v99, vcc
	global_load_dwordx4 v[70:73], v[74:75], off offset:-4096
	v_mul_f32_e32 v78, v153, v160
	v_or_b32_e32 v76, 16, v154
	v_lshl_add_u64 v[90:91], v[174:175], 0, v[164:165]
	v_lshl_add_u64 v[90:91], v[90:91], 0, v[252:253]
	v_ashrrev_i32_e32 v77, 31, v76
	v_mul_f32_e32 v88, v153, v162
	v_lshlrev_b64 v[76:77], 11, v[76:77]
	v_lshl_add_u64 v[76:77], v[174:175], 0, v[76:77]
	v_lshl_add_u64 v[76:77], v[76:77], 0, v[252:253]
	s_waitcnt vmcnt(4)
	v_pk_mul_f32 v[92:93], v[60:61], v[86:87]
	v_pk_mul_f32 v[94:95], v[58:59], v[84:85]
	v_pk_mul_f32 v[96:97], v[64:65], v[86:87]
	v_pk_mul_f32 v[100:101], v[62:63], v[84:85]
	v_pk_mul_f32 v[102:103], v[52:53], v[86:87]
	v_pk_mul_f32 v[104:105], v[50:51], v[84:85]
	v_pk_mul_f32 v[86:87], v[56:57], v[86:87]
	v_pk_mul_f32 v[84:85], v[54:55], v[84:85]
	v_pk_fma_f32 v[64:65], v[64:65], v[82:83], v[92:93] neg_lo:[0,0,1] neg_hi:[0,0,1]
	v_pk_fma_f32 v[62:63], v[62:63], v[80:81], v[94:95] neg_lo:[0,0,1] neg_hi:[0,0,1]
	v_pk_fma_f32 v[60:61], v[60:61], v[82:83], v[96:97]
	v_pk_fma_f32 v[58:59], v[58:59], v[80:81], v[100:101]
	v_pk_fma_f32 v[54:55], v[54:55], v[80:81], v[104:105] neg_lo:[0,0,1] neg_hi:[0,0,1]
	v_pk_fma_f32 v[52:53], v[52:53], v[82:83], v[86:87]
	v_pk_fma_f32 v[50:51], v[50:51], v[80:81], v[84:85]
	v_pk_mul_f32 v[64:65], v[78:79], v[64:65] op_sel_hi:[0,1]
	v_pk_mul_f32 v[62:63], v[78:79], v[62:63] op_sel_hi:[0,1]
	v_pk_mul_f32 v[60:61], v[78:79], v[60:61] op_sel_hi:[0,1]
	v_pk_mul_f32 v[58:59], v[78:79], v[58:59] op_sel_hi:[0,1]
	v_pk_fma_f32 v[56:57], v[56:57], v[82:83], v[102:103] neg_lo:[0,0,1] neg_hi:[0,0,1]
	v_pk_mul_f32 v[54:55], v[78:79], v[54:55] op_sel_hi:[0,1]
	v_pk_mul_f32 v[52:53], v[78:79], v[52:53] op_sel_hi:[0,1]
	v_pk_mul_f32 v[50:51], v[78:79], v[50:51] op_sel_hi:[0,1]
	v_cvt_pk_bf16_f32 v248, v62, v63
	v_cvt_pk_bf16_f32 v249, v64, v65
	v_cvt_pk_bf16_f32 v250, v58, v59
	v_cvt_pk_bf16_f32 v251, v60, v61
	s_waitcnt vmcnt(1)
; __device__ __forceinline__ unsigned cvt_pk_bf16(float lo, float hi) { unsigned r; asm volatile("v_cvt_pk_bf16_f32 %0, %1, %2" : "=v"(r) : "v"(lo), "v"(hi)); return r; }
;     __device__ __forceinline__ void operator()(const pg8::f32x4 (&acc)[2][2][4][2], const Unit& u, int wr, int wc, int fr, int fq) const {
;     ...
;         if (pn < rope_tiles) {
;             const float s_ = (pn >= sc_lo && pn < sc_hi) ? sc : 1.f;
;             const int i0 = 16 * (wc & 1) + 4 * fq;
;             f32x4 cN = *(const f32x4*)(cs + (row0 & (SEQL - 1)) * 64 + i0), sN = *(const f32x4*)(cs + (row0 & (SEQL - 1)) * 64 + 32 + i0);
; #pragma unroll
;             for (int k = 0; k < 8; ++k) { const int ai = k >> 2, m = k & 3; const int row = row0 + ai * HALF + m * 16; const float s = s_ * rsv[k];
;                 const f32x4 c = cN, sn = sN;
;                 if (k < 7) { const int rown = row0 + ((k + 1) >> 2) * HALF + ((k + 1) & 3) * 16, posn = rown & (SEQL - 1); cN = *(const f32x4*)(cs + posn * 64 + i0); sN = *(const f32x4*)(cs + posn * 64 + 32 + i0); }
; #pragma unroll
;                 for (int bj = 0; bj < 2; ++bj) { const f32x4 x1 = acc[ai][bj][m][0], x2 = acc[ai][bj][m][1];
;                     const f32x4 o1 = (x1 * c - x2 * sn) * s, o2 = (x2 * c + x1 * sn) * s;
;                     bf16* p = Ob + (size_t)row * ldc + pt * BM + bj * HALF + 64 * (wc >> 1) + i0;
;                     v2u w1, w2; w1.x = cvt_pk_bf16(o1[0], o1[1]); w1.y = cvt_pk_bf16(o1[2], o1[3]); w2.x = cvt_pk_bf16(o2[0], o2[1]); w2.y = cvt_pk_bf16(o2[2], o2[3]);
;                     *(v2u*)p = w1; *(v2u*)(p + 32) = w2; } }
	v_pk_mul_f32 v[60:61], v[44:45], v[68:69]
	v_pk_mul_f32 v[64:65], v[42:43], v[66:67]
	v_pk_mul_f32 v[80:81], v[46:47], v[66:67]
	v_pk_mul_f32 v[56:57], v[78:79], v[56:57] op_sel_hi:[0,1]
	v_pk_mul_f32 v[78:79], v[48:49], v[68:69]
	s_nop 1
	v_permlane16_swap_b32 v248, v250
	v_permlane16_swap_b32 v249, v251
	global_store_dwordx4 v[90:91], v[248:251], off
	v_cvt_pk_bf16_f32 v240, v54, v55
	v_cvt_pk_bf16_f32 v241, v56, v57
	v_cvt_pk_bf16_f32 v242, v50, v51
	v_cvt_pk_bf16_f32 v243, v52, v53
	s_waitcnt vmcnt(1)
	v_pk_fma_f32 v[48:49], v[48:49], v[72:73], v[60:61] neg_lo:[0,0,1] neg_hi:[0,0,1]
	v_pk_fma_f32 v[46:47], v[46:47], v[70:71], v[64:65] neg_lo:[0,0,1] neg_hi:[0,0,1]
	v_pk_fma_f32 v[52:53], v[42:43], v[70:71], v[80:81]
	v_pk_fma_f32 v[44:45], v[44:45], v[72:73], v[78:79]
	s_nop 1
	v_permlane16_swap_b32 v240, v242
	v_permlane16_swap_b32 v241, v243
	global_store_dwordx4 v[90:91], v[240:243], off offset:256
	v_pk_mul_f32 v[50:51], v[88:89], v[48:49] op_sel_hi:[0,1]
	v_pk_mul_f32 v[54:55], v[88:89], v[46:47] op_sel_hi:[0,1]
	v_pk_mul_f32 v[52:53], v[88:89], v[52:53] op_sel_hi:[0,1]
	v_pk_mul_f32 v[56:57], v[88:89], v[44:45] op_sel_hi:[0,1]
	global_load_dwordx4 v[42:45], v[74:75], off
	global_load_dwordx4 v[46:49], v[74:75], off offset:128
	v_cvt_pk_bf16_f32 v244, v54, v55
	v_cvt_pk_bf16_f32 v245, v50, v51
	v_cvt_pk_bf16_f32 v246, v52, v53
	v_cvt_pk_bf16_f32 v247, v56, v57
	v_pk_mul_f32 v[52:53], v[34:35], v[66:67]
	s_nop 1
	v_permlane16_swap_b32 v244, v246
	v_permlane16_swap_b32 v245, v247
	global_store_dwordx4 v[76:77], v[244:247], off
	v_pk_mul_f32 v[50:51], v[36:37], v[68:69]
	v_pk_fma_f32 v[52:53], v[38:39], v[70:71], v[52:53] neg_lo:[0,0,1] neg_hi:[0,0,1]
	v_pk_mul_f32 v[38:39], v[38:39], v[66:67]
	v_pk_fma_f32 v[50:51], v[40:41], v[72:73], v[50:51] neg_lo:[0,0,1] neg_hi:[0,0,1]
	v_pk_mul_f32 v[40:41], v[40:41], v[68:69]
	v_pk_fma_f32 v[34:35], v[34:35], v[70:71], v[38:39]
	v_pk_mul_f32 v[50:51], v[88:89], v[50:51] op_sel_hi:[0,1]
	v_pk_mul_f32 v[52:53], v[88:89], v[52:53] op_sel_hi:[0,1]
	v_pk_fma_f32 v[36:37], v[36:37], v[72:73], v[40:41]
	v_pk_mul_f32 v[34:35], v[88:89], v[34:35] op_sel_hi:[0,1]
	v_cvt_pk_bf16_f32 v248, v52, v53
	v_cvt_pk_bf16_f32 v249, v50, v51
	v_pk_mul_f32 v[36:37], v[88:89], v[36:37] op_sel_hi:[0,1]
	v_cvt_pk_bf16_f32 v250, v34, v35
	v_cvt_pk_bf16_f32 v251, v36, v37
	s_nop 1
	v_permlane16_swap_b32 v248, v250
	v_permlane16_swap_b32 v249, v251
	global_store_dwordx4 v[76:77], v[248:251], off offset:256
	v_add_co_u32_e32 v38, vcc, s54, v98
	v_or_b32_e32 v50, 32, v154
	s_nop 0
	v_addc_co_u32_e32 v39, vcc, 0, v99, vcc
	global_load_dwordx4 v[34:37], v[38:39], off offset:128
	s_nop 0
	global_load_dwordx4 v[38:41], v[38:39], off
	v_mul_f32_e32 v54, v153, v156
	v_ashrrev_i32_e32 v51, 31, v50
	v_or_b32_e32 v52, 48, v154
	v_lshlrev_b64 v[50:51], 11, v[50:51]
	v_ashrrev_i32_e32 v53, 31, v52
	v_mul_f32_e32 v56, v153, v158
	v_lshl_add_u64 v[50:51], v[174:175], 0, v[50:51]
	v_lshl_add_u64 v[50:51], v[50:51], 0, v[252:253]
	v_lshlrev_b64 v[52:53], 11, v[52:53]
	v_lshl_add_u64 v[52:53], v[174:175], 0, v[52:53]
	v_lshl_add_u64 v[52:53], v[52:53], 0, v[252:253]
	s_waitcnt vmcnt(4)
	v_pk_mul_f32 v[58:59], v[28:29], v[48:49]
	v_pk_mul_f32 v[60:61], v[26:27], v[46:47]
	v_pk_mul_f32 v[62:63], v[32:33], v[48:49]
	v_pk_mul_f32 v[64:65], v[30:31], v[46:47]
	v_pk_fma_f32 v[32:33], v[32:33], v[44:45], v[58:59] neg_lo:[0,0,1] neg_hi:[0,0,1]
	v_pk_fma_f32 v[30:31], v[30:31], v[42:43], v[60:61] neg_lo:[0,0,1] neg_hi:[0,0,1]
	v_pk_mul_f32 v[66:67], v[20:21], v[48:49]
	v_pk_mul_f32 v[68:69], v[18:19], v[46:47]
	v_pk_mul_f32 v[48:49], v[24:25], v[48:49]
	v_pk_mul_f32 v[46:47], v[22:23], v[46:47]
	v_pk_fma_f32 v[28:29], v[28:29], v[44:45], v[62:63]
	v_pk_fma_f32 v[26:27], v[26:27], v[42:43], v[64:65]
	v_pk_mul_f32 v[32:33], v[54:55], v[32:33] op_sel_hi:[0,1]
	v_pk_mul_f32 v[30:31], v[54:55], v[30:31] op_sel_hi:[0,1]
	v_pk_fma_f32 v[24:25], v[24:25], v[44:45], v[66:67] neg_lo:[0,0,1] neg_hi:[0,0,1]
	v_pk_fma_f32 v[22:23], v[22:23], v[42:43], v[68:69] neg_lo:[0,0,1] neg_hi:[0,0,1]
	v_pk_fma_f32 v[20:21], v[20:21], v[44:45], v[48:49]
	v_pk_fma_f32 v[18:19], v[18:19], v[42:43], v[46:47]
	v_pk_mul_f32 v[28:29], v[54:55], v[28:29] op_sel_hi:[0,1]
	v_pk_mul_f32 v[26:27], v[54:55], v[26:27] op_sel_hi:[0,1]
	v_cvt_pk_bf16_f32 v240, v30, v31
	v_cvt_pk_bf16_f32 v241, v32, v33
	v_pk_mul_f32 v[22:23], v[54:55], v[22:23] op_sel_hi:[0,1]
	v_cvt_pk_bf16_f32 v242, v26, v27
	v_cvt_pk_bf16_f32 v243, v28, v29
	v_pk_mul_f32 v[24:25], v[54:55], v[24:25] op_sel_hi:[0,1]
	v_pk_mul_f32 v[18:19], v[54:55], v[18:19] op_sel_hi:[0,1]
	s_waitcnt vmcnt(1)
	v_pk_mul_f32 v[32:33], v[10:11], v[34:35]
	v_pk_mul_f32 v[42:43], v[16:17], v[36:37]
	v_pk_mul_f32 v[44:45], v[14:15], v[34:35]
	v_pk_mul_f32 v[28:29], v[12:13], v[36:37]
	s_waitcnt vmcnt(0)
	v_pk_fma_f32 v[14:15], v[14:15], v[38:39], v[32:33] neg_lo:[0,0,1] neg_hi:[0,0,1]
	v_pk_fma_f32 v[12:13], v[12:13], v[40:41], v[42:43]
	v_pk_fma_f32 v[10:11], v[10:11], v[38:39], v[44:45]
	s_nop 1
	v_permlane16_swap_b32 v240, v242
	v_permlane16_swap_b32 v241, v243
	global_store_dwordx4 v[50:51], v[240:243], off
	v_cvt_pk_bf16_f32 v244, v22, v23
	v_cvt_pk_bf16_f32 v245, v24, v25
	v_pk_fma_f32 v[16:17], v[16:17], v[40:41], v[28:29] neg_lo:[0,0,1] neg_hi:[0,0,1]
	v_pk_mul_f32 v[14:15], v[56:57], v[14:15] op_sel_hi:[0,1]
	v_pk_mul_f32 v[12:13], v[56:57], v[12:13] op_sel_hi:[0,1]
	v_pk_mul_f32 v[10:11], v[56:57], v[10:11] op_sel_hi:[0,1]
	v_pk_mul_f32 v[20:21], v[54:55], v[20:21] op_sel_hi:[0,1]
	v_cvt_pk_bf16_f32 v246, v18, v19
	v_cvt_pk_bf16_f32 v247, v20, v21
	s_nop 1
	v_permlane16_swap_b32 v244, v246
	v_permlane16_swap_b32 v245, v247
	global_store_dwordx4 v[50:51], v[244:247], off offset:256
	v_pk_mul_f32 v[16:17], v[56:57], v[16:17] op_sel_hi:[0,1]
	v_cvt_pk_bf16_f32 v248, v14, v15
	v_cvt_pk_bf16_f32 v249, v16, v17
	v_cvt_pk_bf16_f32 v250, v10, v11
	v_cvt_pk_bf16_f32 v251, v12, v13
	v_pk_mul_f32 v[12:13], v[2:3], v[34:35]
	s_nop 1
	v_permlane16_swap_b32 v248, v250
	v_permlane16_swap_b32 v249, v251
	global_store_dwordx4 v[52:53], v[248:251], off
	v_pk_mul_f32 v[10:11], v[4:5], v[36:37]
	v_pk_fma_f32 v[12:13], v[6:7], v[38:39], v[12:13] neg_lo:[0,0,1] neg_hi:[0,0,1]
	v_pk_mul_f32 v[6:7], v[6:7], v[34:35]
	v_pk_fma_f32 v[10:11], v[8:9], v[40:41], v[10:11] neg_lo:[0,0,1] neg_hi:[0,0,1]
	v_pk_mul_f32 v[8:9], v[8:9], v[36:37]
	v_pk_fma_f32 v[2:3], v[2:3], v[38:39], v[6:7]
	v_pk_mul_f32 v[10:11], v[56:57], v[10:11] op_sel_hi:[0,1]
	v_pk_mul_f32 v[12:13], v[56:57], v[12:13] op_sel_hi:[0,1]
	v_pk_fma_f32 v[4:5], v[4:5], v[40:41], v[8:9]
	v_pk_mul_f32 v[2:3], v[56:57], v[2:3] op_sel_hi:[0,1]
	v_cvt_pk_bf16_f32 v240, v12, v13
	v_cvt_pk_bf16_f32 v241, v10, v11
	v_pk_mul_f32 v[4:5], v[56:57], v[4:5] op_sel_hi:[0,1]
	v_cvt_pk_bf16_f32 v242, v2, v3
	v_cvt_pk_bf16_f32 v243, v4, v5
	s_nop 1
	v_permlane16_swap_b32 v240, v242
	v_permlane16_swap_b32 v241, v243
	global_store_dwordx4 v[52:53], v[240:243], off offset:256
	s_andn2_b64 vcc, exec, s[6:7]
	s_mov_b64 s[4:5], -1
	s_cbranch_vccnz .LBB0_985
